# tile scheduler: shift/mask fast path when the group height is 8 (skips the rcp-based division), next-tile-valid mask built with one s_andn2 instead of cndmask+cmp
# baseline (speedup 1.0000x reference)
;     DI bool next(int i, Unit& u) const {
;     ...
;         const int nig = WGM * nN, gid = wgid / nig, fm = gid * WGM, gsz = (nM - fm) < WGM ? (nM - fm) : WGM;
;         u.pm = fm + ((wgid % nig) % gsz); u.pn = (wgid % nig) / gsz; return true;
.LBB0_785:
	s_abs_i32 s1, s3
	s_mul_hi_u32 s4, s1, s93
	s_mul_i32 s5, s4, s92
	s_ashr_i32 s0, s3, 31
	s_sub_i32 s1, s1, s5
	s_xor_b32 s0, s0, s54
	s_add_i32 s5, s4, 1
	s_sub_i32 s26, s1, s92
	s_cmp_ge_u32 s1, s92
	s_cselect_b32 s4, s5, s4
	s_cselect_b32 s1, s26, s1
	s_add_i32 s5, s4, 1
	s_cmp_ge_u32 s1, s92
	s_cselect_b32 s1, s5, s4
	s_xor_b32 s1, s1, s0
	s_sub_i32 s0, s1, s0
	s_lshl_b32 s1, s0, 3
	s_sub_i32 s4, s89, s1
	s_min_i32 s4, s4, 8
	s_cmp_eq_u32 s4, 8
	s_cbranch_scc1 .Lg_div8
	s_abs_i32 s5, s4
	v_cvt_f32_u32_e32 v2, s5
	s_sub_i32 s28, 0, s5
	s_mul_i32 s0, s0, s43
	s_sub_i32 s0, s3, s0
	v_rcp_iflag_f32_e32 v2, v2
	s_abs_i32 s27, s0
	s_xor_b32 s26, s0, s4
	s_ashr_i32 s26, s26, 31
	v_mul_f32_e32 v2, 0x4f7ffffe, v2
	v_cvt_u32_f32_e32 v2, v2
	s_nop 0
	v_readfirstlane_b32 s29, v2
	s_mul_i32 s28, s28, s29
	s_mul_hi_u32 s28, s29, s28
	s_add_i32 s29, s29, s28
	s_mul_hi_u32 s28, s27, s29
	s_mul_i32 s29, s28, s5
	s_sub_i32 s27, s27, s29
	s_add_i32 s29, s28, 1
	s_sub_i32 s33, s27, s5
	s_cmp_ge_u32 s27, s5
	s_cselect_b32 s28, s29, s28
	s_cselect_b32 s27, s33, s27
	s_add_i32 s29, s28, 1
	s_cmp_ge_u32 s27, s5
	s_cselect_b32 s5, s29, s28
	s_xor_b32 s5, s5, s26
	s_sub_i32 s62, s5, s26
	s_mul_i32 s4, s62, s4
	s_sub_i32 s0, s0, s4
	s_add_i32 s63, s0, s1
	s_cbranch_execnz .LBB0_787
	s_branch .LBB0_786
.Lg_div8:
	s_mul_i32 s0, s0, s43
	s_sub_i32 s0, s3, s0
	s_ashr_i32 s62, s0, 3
	s_and_b32 s4, s0, 7
	s_add_i32 s63, s4, s1
	s_branch .LBB0_787
